# sample_combine rewritten by hand: (m,l) of the 25 partials handled lane-parallel with DPP row reductions, partial outputs all in flight, f32 rcp instead of IEEE division
# speedup vs baseline: 1.0653x; 1.0065x over previous
; __device__ __forceinline__ void sample_combine(const Ctx& c, int l, int bn, int lane) {
;     const int n = bn & 1, b = bn >> 1, row = MPR + b;
;     const float* pt = (const float*)(AWS + WS_PART) + (size_t)bn * 25 * 264; const float* HS = (const float*)(AWS + WS_HS); const float* oc = (const float*)(AWS + WS_OCMP) + (size_t)bn * 256;
;     float res[2][4];
; #pragma unroll
;     for (int br = 0; br < 2; ++br) { const int p0 = br ? 16 : 0, np = br ? 9 : 16;
;         float M[4] = {NEGV, NEGV, NEGV, NEGV};
; #pragma unroll 4
;         for (int k = 0; k < np; ++k) { const f32x4 mv = *(const f32x4*)(pt + (size_t)(p0 + k) * 264);
.LBB0_1511:
	v_readlane_b32 s16, v254, 46
	v_mbcnt_lo_u32_b32 v18, -1, 0
	v_mbcnt_hi_u32_b32 v18, -1, v18
	v_readlane_b32 s17, v253, 17
	ds_read_b32 v0, v1 offset:464
	ds_read_b32 v6, v1 offset:468
	ds_read_b32 v7, v1 offset:464
	ds_read_b32 v8, v1 offset:468
	ds_read_b32 v9, v1 offset:464
	ds_read_b32 v10, v1 offset:468
	ds_read_b32 v2, v1 offset:384
	ds_read_b32 v3, v1 offset:388
	v_add_u32_e32 v4, s0, v18
	v_ashrrev_i32_e32 v5, 31, v4
	s_waitcnt lgkmcnt(0)
	v_readfirstlane_b32 s23, v0
	v_readfirstlane_b32 s2, v2
	v_readfirstlane_b32 s3, v3
	v_readfirstlane_b32 s24, v6
	v_mov_b32_e32 v2, s2
	v_mov_b32_e32 v3, s3
	v_lshl_add_u64 v[2:3], v[4:5], 2, v[2:3]
	global_load_dword v36, v[2:3], off
	s_lshl_b32 s2, s17, 3
	s_add_i32 s12, s2, s16
	v_readfirstlane_b32 s13, v7
	v_readfirstlane_b32 s18, v8
	v_readfirstlane_b32 s19, v9
	v_readfirstlane_b32 s22, v10
	s_cmpk_gt_i32 s12, 0xff
	v_ashrrev_i32_e32 v19, 31, v18
	s_cbranch_scc1 .LBB0_1526
	v_readlane_b32 s39, v253, 3
	s_lshl_b32 s39, s39, 3
	s_mov_b32 s20, s12
	v_lshlrev_b32_e32 v41, 2, v18
	v_min_u32_e32 v40, 24, v18
	v_mul_u32_u24_e32 v40, 0x420, v40
	v_cmp_gt_u32_e64 s[36:37], 25, v18
.Lsc_loop:
	s_mul_i32 s2, s20, 0x6720
	s_add_u32 s4, s23, 0x43100000
	s_addc_u32 s5, s24, 0
	s_add_u32 s4, s4, s2
	s_addc_u32 s5, s5, 0
	global_load_dwordx4 v[44:47], v40, s[4:5]
	global_load_dwordx4 v[48:51], v40, s[4:5] offset:16
	s_add_u32 s6, s4, 0x0
	s_addc_u32 s7, s5, 0
	global_load_dword v60, v41, s[6:7] offset:32
	global_load_dword v61, v41, s[6:7] offset:288
	global_load_dword v62, v41, s[6:7] offset:544
	global_load_dword v63, v41, s[6:7] offset:800
	s_add_u32 s6, s4, 0x420
	s_addc_u32 s7, s5, 0
	global_load_dword v64, v41, s[6:7] offset:32
	global_load_dword v65, v41, s[6:7] offset:288
	global_load_dword v66, v41, s[6:7] offset:544
	global_load_dword v67, v41, s[6:7] offset:800
	s_add_u32 s6, s4, 0x840
	s_addc_u32 s7, s5, 0
	global_load_dword v68, v41, s[6:7] offset:32
	global_load_dword v69, v41, s[6:7] offset:288
	global_load_dword v70, v41, s[6:7] offset:544
	global_load_dword v71, v41, s[6:7] offset:800
	s_add_u32 s6, s4, 0xc60
	s_addc_u32 s7, s5, 0
	global_load_dword v72, v41, s[6:7] offset:32
	global_load_dword v73, v41, s[6:7] offset:288
	global_load_dword v74, v41, s[6:7] offset:544
	global_load_dword v75, v41, s[6:7] offset:800
	s_add_u32 s6, s4, 0x1080
	s_addc_u32 s7, s5, 0
	global_load_dword v76, v41, s[6:7] offset:32
	global_load_dword v77, v41, s[6:7] offset:288
	global_load_dword v78, v41, s[6:7] offset:544
	global_load_dword v79, v41, s[6:7] offset:800
	s_add_u32 s6, s4, 0x14a0
	s_addc_u32 s7, s5, 0
	global_load_dword v80, v41, s[6:7] offset:32
	global_load_dword v81, v41, s[6:7] offset:288
	global_load_dword v82, v41, s[6:7] offset:544
	global_load_dword v83, v41, s[6:7] offset:800
	s_add_u32 s6, s4, 0x18c0
	s_addc_u32 s7, s5, 0
	global_load_dword v84, v41, s[6:7] offset:32
	global_load_dword v85, v41, s[6:7] offset:288
	global_load_dword v86, v41, s[6:7] offset:544
	global_load_dword v87, v41, s[6:7] offset:800
	s_add_u32 s6, s4, 0x1ce0
	s_addc_u32 s7, s5, 0
	global_load_dword v88, v41, s[6:7] offset:32
	global_load_dword v89, v41, s[6:7] offset:288
	global_load_dword v90, v41, s[6:7] offset:544
	global_load_dword v91, v41, s[6:7] offset:800
	s_add_u32 s6, s4, 0x2100
	s_addc_u32 s7, s5, 0
	global_load_dword v92, v41, s[6:7] offset:32
	global_load_dword v93, v41, s[6:7] offset:288
	global_load_dword v94, v41, s[6:7] offset:544
	global_load_dword v95, v41, s[6:7] offset:800
	s_add_u32 s6, s4, 0x2520
	s_addc_u32 s7, s5, 0
	global_load_dword v96, v41, s[6:7] offset:32
	global_load_dword v97, v41, s[6:7] offset:288
	global_load_dword v98, v41, s[6:7] offset:544
	global_load_dword v99, v41, s[6:7] offset:800
	s_add_u32 s6, s4, 0x2940
	s_addc_u32 s7, s5, 0
	global_load_dword v100, v41, s[6:7] offset:32
	global_load_dword v101, v41, s[6:7] offset:288
	global_load_dword v102, v41, s[6:7] offset:544
	global_load_dword v103, v41, s[6:7] offset:800
	s_add_u32 s6, s4, 0x2d60
	s_addc_u32 s7, s5, 0
	global_load_dword v104, v41, s[6:7] offset:32
	global_load_dword v105, v41, s[6:7] offset:288
	global_load_dword v106, v41, s[6:7] offset:544
	global_load_dword v107, v41, s[6:7] offset:800
	s_add_u32 s6, s4, 0x3180
	s_addc_u32 s7, s5, 0
	global_load_dword v108, v41, s[6:7] offset:32
	global_load_dword v109, v41, s[6:7] offset:288
	global_load_dword v110, v41, s[6:7] offset:544
	global_load_dword v111, v41, s[6:7] offset:800
	s_add_u32 s6, s4, 0x35a0
	s_addc_u32 s7, s5, 0
	global_load_dword v112, v41, s[6:7] offset:32
	global_load_dword v113, v41, s[6:7] offset:288
	global_load_dword v114, v41, s[6:7] offset:544
	global_load_dword v115, v41, s[6:7] offset:800
	s_add_u32 s6, s4, 0x39c0
	s_addc_u32 s7, s5, 0
	global_load_dword v116, v41, s[6:7] offset:32
	global_load_dword v117, v41, s[6:7] offset:288
	global_load_dword v118, v41, s[6:7] offset:544
	global_load_dword v119, v41, s[6:7] offset:800
	s_waitcnt vmcnt(60)
; __device__ __forceinline__ void sample_combine(const Ctx& c, int l, int bn, int lane) {
;     ...
;     for (int br = 0; br < 2; ++br) { const int p0 = br ? 16 : 0, np = br ? 9 : 16;
;         float M[4] = {NEGV, NEGV, NEGV, NEGV};
; #pragma unroll 4
;         for (int k = 0; k < np; ++k) { const f32x4 mv = *(const f32x4*)(pt + (size_t)(p0 + k) * 264);
; #pragma unroll
;             for (int g = 0; g < 4; ++g) M[g] = fmaxf(M[g], mv[g]); }
;         float L[4] = {0.f, 0.f, 0.f, 0.f}, O[4] = {0.f, 0.f, 0.f, 0.f};
; #pragma unroll 4
;         for (int k = 0; k < np; ++k) { const float* pp = pt + (size_t)(p0 + k) * 264; const f32x4 mv = *(const f32x4*)pp, lv = *(const f32x4*)(pp + 4);
; #pragma unroll
;             for (int g = 0; g < 4; ++g) { const float f = __expf(mv[g] - M[g]); L[g] += lv[g] * f; O[g] += pp[8 + g * 64 + lane] * f; } }
	v_mov_b32_e32 v174, 0xf149f2ca
	v_mov_b32_e32 v175, 0xf149f2ca
	v_mov_b32_e32 v176, 0xf149f2ca
	v_mov_b32_e32 v177, 0xf149f2ca
	v_cndmask_b32_e64 v44, v174, v44, s[36:37]
	v_cndmask_b32_e64 v48, 0, v48, s[36:37]
	v_cndmask_b32_e64 v45, v175, v45, s[36:37]
	v_cndmask_b32_e64 v49, 0, v49, s[36:37]
	v_cndmask_b32_e64 v46, v176, v46, s[36:37]
	v_cndmask_b32_e64 v50, 0, v50, s[36:37]
	v_cndmask_b32_e64 v47, v177, v47, s[36:37]
	v_cndmask_b32_e64 v51, 0, v51, s[36:37]
	v_mov_b32_e32 v52, v44
	v_mov_b32_e32 v53, v45
	v_mov_b32_e32 v54, v46
	v_mov_b32_e32 v55, v47
	v_max_f32_dpp v52, v52, v52 quad_perm:[1,0,3,2] row_mask:0xf bank_mask:0xf bound_ctrl:1
	v_max_f32_dpp v53, v53, v53 quad_perm:[1,0,3,2] row_mask:0xf bank_mask:0xf bound_ctrl:1
	v_max_f32_dpp v54, v54, v54 quad_perm:[1,0,3,2] row_mask:0xf bank_mask:0xf bound_ctrl:1
	v_max_f32_dpp v55, v55, v55 quad_perm:[1,0,3,2] row_mask:0xf bank_mask:0xf bound_ctrl:1
	v_max_f32_dpp v52, v52, v52 quad_perm:[2,3,0,1] row_mask:0xf bank_mask:0xf bound_ctrl:1
	v_max_f32_dpp v53, v53, v53 quad_perm:[2,3,0,1] row_mask:0xf bank_mask:0xf bound_ctrl:1
	v_max_f32_dpp v54, v54, v54 quad_perm:[2,3,0,1] row_mask:0xf bank_mask:0xf bound_ctrl:1
	v_max_f32_dpp v55, v55, v55 quad_perm:[2,3,0,1] row_mask:0xf bank_mask:0xf bound_ctrl:1
	v_max_f32_dpp v52, v52, v52 row_half_mirror row_mask:0xf bank_mask:0xf bound_ctrl:1
	v_max_f32_dpp v53, v53, v53 row_half_mirror row_mask:0xf bank_mask:0xf bound_ctrl:1
	v_max_f32_dpp v54, v54, v54 row_half_mirror row_mask:0xf bank_mask:0xf bound_ctrl:1
	v_max_f32_dpp v55, v55, v55 row_half_mirror row_mask:0xf bank_mask:0xf bound_ctrl:1
	v_max_f32_dpp v52, v52, v52 row_mirror row_mask:0xf bank_mask:0xf bound_ctrl:1
	v_max_f32_dpp v53, v53, v53 row_mirror row_mask:0xf bank_mask:0xf bound_ctrl:1
	v_max_f32_dpp v54, v54, v54 row_mirror row_mask:0xf bank_mask:0xf bound_ctrl:1
	v_max_f32_dpp v55, v55, v55 row_mirror row_mask:0xf bank_mask:0xf bound_ctrl:1
	v_sub_f32_e32 v52, v44, v52
	v_sub_f32_e32 v53, v45, v53
	v_sub_f32_e32 v54, v46, v54
	v_sub_f32_e32 v55, v47, v55
	v_mul_f32_e32 v52, 0x3fb8aa3b, v52
	v_mul_f32_e32 v53, 0x3fb8aa3b, v53
	v_mul_f32_e32 v54, 0x3fb8aa3b, v54
	v_mul_f32_e32 v55, 0x3fb8aa3b, v55
	v_exp_f32_e32 v52, v52
	v_exp_f32_e32 v53, v53
	v_exp_f32_e32 v54, v54
	v_exp_f32_e32 v55, v55
	v_mul_f32_e32 v56, v48, v52
	v_mul_f32_e32 v57, v49, v53
	v_mul_f32_e32 v58, v50, v54
	v_mul_f32_e32 v59, v51, v55
	v_add_f32_dpp v56, v56, v56 quad_perm:[1,0,3,2] row_mask:0xf bank_mask:0xf bound_ctrl:1
	v_add_f32_dpp v57, v57, v57 quad_perm:[1,0,3,2] row_mask:0xf bank_mask:0xf bound_ctrl:1
	v_add_f32_dpp v58, v58, v58 quad_perm:[1,0,3,2] row_mask:0xf bank_mask:0xf bound_ctrl:1
	v_add_f32_dpp v59, v59, v59 quad_perm:[1,0,3,2] row_mask:0xf bank_mask:0xf bound_ctrl:1
	v_add_f32_dpp v56, v56, v56 quad_perm:[2,3,0,1] row_mask:0xf bank_mask:0xf bound_ctrl:1
	v_add_f32_dpp v57, v57, v57 quad_perm:[2,3,0,1] row_mask:0xf bank_mask:0xf bound_ctrl:1
	v_add_f32_dpp v58, v58, v58 quad_perm:[2,3,0,1] row_mask:0xf bank_mask:0xf bound_ctrl:1
	v_add_f32_dpp v59, v59, v59 quad_perm:[2,3,0,1] row_mask:0xf bank_mask:0xf bound_ctrl:1
	v_add_f32_dpp v56, v56, v56 row_half_mirror row_mask:0xf bank_mask:0xf bound_ctrl:1
	v_add_f32_dpp v57, v57, v57 row_half_mirror row_mask:0xf bank_mask:0xf bound_ctrl:1
	v_add_f32_dpp v58, v58, v58 row_half_mirror row_mask:0xf bank_mask:0xf bound_ctrl:1
	v_add_f32_dpp v59, v59, v59 row_half_mirror row_mask:0xf bank_mask:0xf bound_ctrl:1
	v_add_f32_dpp v56, v56, v56 row_mirror row_mask:0xf bank_mask:0xf bound_ctrl:1
	v_add_f32_dpp v57, v57, v57 row_mirror row_mask:0xf bank_mask:0xf bound_ctrl:1
	v_add_f32_dpp v58, v58, v58 row_mirror row_mask:0xf bank_mask:0xf bound_ctrl:1
	v_add_f32_dpp v59, v59, v59 row_mirror row_mask:0xf bank_mask:0xf bound_ctrl:1
	v_mov_b32_e32 v160, 0
	v_mov_b32_e32 v161, 0
	v_mov_b32_e32 v162, 0
	v_mov_b32_e32 v163, 0
	v_mov_b32_e32 v164, 0
	v_mov_b32_e32 v165, 0
	v_mov_b32_e32 v166, 0
	v_mov_b32_e32 v167, 0
	s_waitcnt vmcnt(0)
	s_add_u32 s6, s4, 0x3de0
	s_addc_u32 s7, s5, 0
	global_load_dword v120, v41, s[6:7] offset:32
	global_load_dword v121, v41, s[6:7] offset:288
	global_load_dword v122, v41, s[6:7] offset:544
	global_load_dword v123, v41, s[6:7] offset:800
	s_add_u32 s6, s4, 0x4200
	s_addc_u32 s7, s5, 0
	global_load_dword v124, v41, s[6:7] offset:32
	global_load_dword v125, v41, s[6:7] offset:288
	global_load_dword v126, v41, s[6:7] offset:544
	global_load_dword v127, v41, s[6:7] offset:800
	s_add_u32 s6, s4, 0x4620
	s_addc_u32 s7, s5, 0
	global_load_dword v128, v41, s[6:7] offset:32
	global_load_dword v129, v41, s[6:7] offset:288
	global_load_dword v130, v41, s[6:7] offset:544
	global_load_dword v131, v41, s[6:7] offset:800
	s_add_u32 s6, s4, 0x4a40
	s_addc_u32 s7, s5, 0
	global_load_dword v132, v41, s[6:7] offset:32
	global_load_dword v133, v41, s[6:7] offset:288
	global_load_dword v134, v41, s[6:7] offset:544
	global_load_dword v135, v41, s[6:7] offset:800
	s_add_u32 s6, s4, 0x4e60
	s_addc_u32 s7, s5, 0
	global_load_dword v136, v41, s[6:7] offset:32
	global_load_dword v137, v41, s[6:7] offset:288
	global_load_dword v138, v41, s[6:7] offset:544
	global_load_dword v139, v41, s[6:7] offset:800
	s_add_u32 s6, s4, 0x5280
	s_addc_u32 s7, s5, 0
	global_load_dword v140, v41, s[6:7] offset:32
	global_load_dword v141, v41, s[6:7] offset:288
	global_load_dword v142, v41, s[6:7] offset:544
	global_load_dword v143, v41, s[6:7] offset:800
	s_add_u32 s6, s4, 0x56a0
	s_addc_u32 s7, s5, 0
	global_load_dword v144, v41, s[6:7] offset:32
	global_load_dword v145, v41, s[6:7] offset:288
	global_load_dword v146, v41, s[6:7] offset:544
	global_load_dword v147, v41, s[6:7] offset:800
; __device__ __forceinline__ void sample_combine(const Ctx& c, int l, int bn, int lane) {
;     ...
;         for (int k = 0; k < np; ++k) { const float* pp = pt + (size_t)(p0 + k) * 264; const f32x4 mv = *(const f32x4*)pp, lv = *(const f32x4*)(pp + 4);
; #pragma unroll
;             for (int g = 0; g < 4; ++g) { const float f = __expf(mv[g] - M[g]); L[g] += lv[g] * f; O[g] += pp[8 + g * 64 + lane] * f; } }
;     ...
;     for (int g = 0; g < 4; ++g) { const int hq = n * 4 + g; const float* gp = HS + (size_t)row * 64 + hq * 3;
	s_add_u32 s6, s4, 0x5ac0
	s_addc_u32 s7, s5, 0
	global_load_dword v148, v41, s[6:7] offset:32
	global_load_dword v149, v41, s[6:7] offset:288
	global_load_dword v150, v41, s[6:7] offset:544
	global_load_dword v151, v41, s[6:7] offset:800
	s_add_u32 s6, s4, 0x5ee0
	s_addc_u32 s7, s5, 0
	global_load_dword v152, v41, s[6:7] offset:32
	global_load_dword v153, v41, s[6:7] offset:288
	global_load_dword v154, v41, s[6:7] offset:544
	global_load_dword v155, v41, s[6:7] offset:800
	s_add_u32 s6, s4, 0x6300
	s_addc_u32 s7, s5, 0
	global_load_dword v156, v41, s[6:7] offset:32
	global_load_dword v157, v41, s[6:7] offset:288
	global_load_dword v158, v41, s[6:7] offset:544
	global_load_dword v159, v41, s[6:7] offset:800
	s_lshr_b32 s2, s20, 1
	s_add_i32 s2, s2, 0x4000
	s_lshl_b32 s3, s2, 8
	s_and_b32 s6, s20, 1
	s_mul_i32 s6, s6, 48
	s_add_i32 s3, s3, s6
	s_add_u32 s6, s13, 0x16f00000
	s_addc_u32 s7, s18, 0
	s_add_u32 s6, s6, s3
	s_addc_u32 s7, s7, 0
	v_min_u32_e32 v42, 11, v18
	v_lshlrev_b32_e32 v42, 2, v42
	global_load_dword v168, v42, s[6:7]
	s_lshl_b32 s3, s20, 10
	s_add_u32 s6, s19, 0x43000000
	s_addc_u32 s7, s22, 0
	s_add_u32 s6, s6, s3
	s_addc_u32 s7, s7, 0
	global_load_dword v170, v41, s[6:7] offset:0
	global_load_dword v171, v41, s[6:7] offset:256
	global_load_dword v172, v41, s[6:7] offset:512
	global_load_dword v173, v41, s[6:7] offset:768
	v_readlane_b32 s8, v52, 0
	v_readlane_b32 s9, v53, 0
	v_readlane_b32 s10, v54, 0
	v_readlane_b32 s11, v55, 0
	v_fmac_f32_e32 v160, s8, v60
	v_fmac_f32_e32 v161, s9, v61
	v_fmac_f32_e32 v162, s10, v62
	v_fmac_f32_e32 v163, s11, v63
	v_readlane_b32 s25, v52, 1
	v_readlane_b32 s26, v53, 1
	v_readlane_b32 s27, v54, 1
	v_readlane_b32 s28, v55, 1
	v_fmac_f32_e32 v160, s25, v64
	v_fmac_f32_e32 v161, s26, v65
	v_fmac_f32_e32 v162, s27, v66
	v_fmac_f32_e32 v163, s28, v67
	v_readlane_b32 s8, v52, 2
	v_readlane_b32 s9, v53, 2
	v_readlane_b32 s10, v54, 2
	v_readlane_b32 s11, v55, 2
	v_fmac_f32_e32 v160, s8, v68
	v_fmac_f32_e32 v161, s9, v69
	v_fmac_f32_e32 v162, s10, v70
	v_fmac_f32_e32 v163, s11, v71
	v_readlane_b32 s25, v52, 3
	v_readlane_b32 s26, v53, 3
	v_readlane_b32 s27, v54, 3
	v_readlane_b32 s28, v55, 3
	v_fmac_f32_e32 v160, s25, v72
	v_fmac_f32_e32 v161, s26, v73
	v_fmac_f32_e32 v162, s27, v74
	v_fmac_f32_e32 v163, s28, v75
	v_readlane_b32 s8, v52, 4
	v_readlane_b32 s9, v53, 4
	v_readlane_b32 s10, v54, 4
	v_readlane_b32 s11, v55, 4
	v_fmac_f32_e32 v160, s8, v76
	v_fmac_f32_e32 v161, s9, v77
	v_fmac_f32_e32 v162, s10, v78
	v_fmac_f32_e32 v163, s11, v79
	v_readlane_b32 s25, v52, 5
	v_readlane_b32 s26, v53, 5
	v_readlane_b32 s27, v54, 5
	v_readlane_b32 s28, v55, 5
	v_fmac_f32_e32 v160, s25, v80
	v_fmac_f32_e32 v161, s26, v81
	v_fmac_f32_e32 v162, s27, v82
	v_fmac_f32_e32 v163, s28, v83
	v_readlane_b32 s8, v52, 6
	v_readlane_b32 s9, v53, 6
	v_readlane_b32 s10, v54, 6
	v_readlane_b32 s11, v55, 6
	v_fmac_f32_e32 v160, s8, v84
	v_fmac_f32_e32 v161, s9, v85
	v_fmac_f32_e32 v162, s10, v86
	v_fmac_f32_e32 v163, s11, v87
	v_readlane_b32 s25, v52, 7
	v_readlane_b32 s26, v53, 7
	v_readlane_b32 s27, v54, 7
	v_readlane_b32 s28, v55, 7
	v_fmac_f32_e32 v160, s25, v88
	v_fmac_f32_e32 v161, s26, v89
	v_fmac_f32_e32 v162, s27, v90
	v_fmac_f32_e32 v163, s28, v91
	v_readlane_b32 s8, v52, 8
	v_readlane_b32 s9, v53, 8
	v_readlane_b32 s10, v54, 8
	v_readlane_b32 s11, v55, 8
	v_fmac_f32_e32 v160, s8, v92
	v_fmac_f32_e32 v161, s9, v93
	v_fmac_f32_e32 v162, s10, v94
	v_fmac_f32_e32 v163, s11, v95
	v_readlane_b32 s25, v52, 9
	v_readlane_b32 s26, v53, 9
	v_readlane_b32 s27, v54, 9
	v_readlane_b32 s28, v55, 9
	v_fmac_f32_e32 v160, s25, v96
	v_fmac_f32_e32 v161, s26, v97
	v_fmac_f32_e32 v162, s27, v98
	v_fmac_f32_e32 v163, s28, v99
	v_readlane_b32 s8, v52, 10
	v_readlane_b32 s9, v53, 10
	v_readlane_b32 s10, v54, 10
	v_readlane_b32 s11, v55, 10
	v_fmac_f32_e32 v160, s8, v100
	v_fmac_f32_e32 v161, s9, v101
	v_fmac_f32_e32 v162, s10, v102
	v_fmac_f32_e32 v163, s11, v103
	v_readlane_b32 s25, v52, 11
	v_readlane_b32 s26, v53, 11
	v_readlane_b32 s27, v54, 11
	v_readlane_b32 s28, v55, 11
	v_fmac_f32_e32 v160, s25, v104
	v_fmac_f32_e32 v161, s26, v105
	v_fmac_f32_e32 v162, s27, v106
	v_fmac_f32_e32 v163, s28, v107
	v_readlane_b32 s8, v52, 12
	v_readlane_b32 s9, v53, 12
	v_readlane_b32 s10, v54, 12
	v_readlane_b32 s11, v55, 12
	v_fmac_f32_e32 v160, s8, v108
	v_fmac_f32_e32 v161, s9, v109
	v_fmac_f32_e32 v162, s10, v110
	v_fmac_f32_e32 v163, s11, v111
	v_readlane_b32 s25, v52, 13
	v_readlane_b32 s26, v53, 13
	v_readlane_b32 s27, v54, 13
	v_readlane_b32 s28, v55, 13
	v_fmac_f32_e32 v160, s25, v112
	v_fmac_f32_e32 v161, s26, v113
	v_fmac_f32_e32 v162, s27, v114
	v_fmac_f32_e32 v163, s28, v115
	v_readlane_b32 s8, v52, 14
	v_readlane_b32 s9, v53, 14
	v_readlane_b32 s10, v54, 14
	v_readlane_b32 s11, v55, 14
	v_fmac_f32_e32 v160, s8, v116
	v_fmac_f32_e32 v161, s9, v117
	v_fmac_f32_e32 v162, s10, v118
	v_fmac_f32_e32 v163, s11, v119
	s_waitcnt vmcnt(0)
; __device__ __forceinline__ unsigned f2bf(float f) { unsigned u = __float_as_uint(f); return (u + 0x7fffu + ((u >> 16) & 1u)) >> 16; }
; __device__ __forceinline__ float sigmoidf_(float x) { return 1.0f / (1.0f + __expf(-x)); }
; __device__ __forceinline__ void sample_combine(const Ctx& c, int l, int bn, int lane) {
;     ...
;         for (int k = 0; k < np; ++k) { const float* pp = pt + (size_t)(p0 + k) * 264; const f32x4 mv = *(const f32x4*)pp, lv = *(const f32x4*)(pp + 4);
; #pragma unroll
;             for (int g = 0; g < 4; ++g) { const float f = __expf(mv[g] - M[g]); L[g] += lv[g] * f; O[g] += pp[8 + g * 64 + lane] * f; } }
; #pragma unroll
;         for (int g = 0; g < 4; ++g) res[br][g] = L[g] > 0.f ? O[g] / L[g] : 0.f; }
;     bf16* MIX = (bf16*)(AWS + WS_MIX);
; #pragma unroll
;     for (int g = 0; g < 4; ++g) { const int hq = n * 4 + g; const float* gp = HS + (size_t)row * 64 + hq * 3;
;         MIX[(size_t)row * DM + hq * 64 + lane] = (bf16)f2bf(sigmoidf_(gp[0]) * oc[g * 64 + lane] + sigmoidf_(gp[1]) * res[0][g] + sigmoidf_(gp[2]) * res[1][g]); }
	v_readlane_b32 s25, v52, 15
	v_readlane_b32 s26, v53, 15
	v_readlane_b32 s27, v54, 15
	v_readlane_b32 s28, v55, 15
	v_fmac_f32_e32 v160, s25, v120
	v_fmac_f32_e32 v161, s26, v121
	v_fmac_f32_e32 v162, s27, v122
	v_fmac_f32_e32 v163, s28, v123
	v_readlane_b32 s8, v52, 16
	v_readlane_b32 s9, v53, 16
	v_readlane_b32 s10, v54, 16
	v_readlane_b32 s11, v55, 16
	v_fmac_f32_e32 v164, s8, v124
	v_fmac_f32_e32 v165, s9, v125
	v_fmac_f32_e32 v166, s10, v126
	v_fmac_f32_e32 v167, s11, v127
	v_readlane_b32 s25, v52, 17
	v_readlane_b32 s26, v53, 17
	v_readlane_b32 s27, v54, 17
	v_readlane_b32 s28, v55, 17
	v_fmac_f32_e32 v164, s25, v128
	v_fmac_f32_e32 v165, s26, v129
	v_fmac_f32_e32 v166, s27, v130
	v_fmac_f32_e32 v167, s28, v131
	v_readlane_b32 s8, v52, 18
	v_readlane_b32 s9, v53, 18
	v_readlane_b32 s10, v54, 18
	v_readlane_b32 s11, v55, 18
	v_fmac_f32_e32 v164, s8, v132
	v_fmac_f32_e32 v165, s9, v133
	v_fmac_f32_e32 v166, s10, v134
	v_fmac_f32_e32 v167, s11, v135
	v_readlane_b32 s25, v52, 19
	v_readlane_b32 s26, v53, 19
	v_readlane_b32 s27, v54, 19
	v_readlane_b32 s28, v55, 19
	v_fmac_f32_e32 v164, s25, v136
	v_fmac_f32_e32 v165, s26, v137
	v_fmac_f32_e32 v166, s27, v138
	v_fmac_f32_e32 v167, s28, v139
	v_readlane_b32 s8, v52, 20
	v_readlane_b32 s9, v53, 20
	v_readlane_b32 s10, v54, 20
	v_readlane_b32 s11, v55, 20
	v_fmac_f32_e32 v164, s8, v140
	v_fmac_f32_e32 v165, s9, v141
	v_fmac_f32_e32 v166, s10, v142
	v_fmac_f32_e32 v167, s11, v143
	v_readlane_b32 s25, v52, 21
	v_readlane_b32 s26, v53, 21
	v_readlane_b32 s27, v54, 21
	v_readlane_b32 s28, v55, 21
	v_fmac_f32_e32 v164, s25, v144
	v_fmac_f32_e32 v165, s26, v145
	v_fmac_f32_e32 v166, s27, v146
	v_fmac_f32_e32 v167, s28, v147
	v_readlane_b32 s8, v52, 22
	v_readlane_b32 s9, v53, 22
	v_readlane_b32 s10, v54, 22
	v_readlane_b32 s11, v55, 22
	v_fmac_f32_e32 v164, s8, v148
	v_fmac_f32_e32 v165, s9, v149
	v_fmac_f32_e32 v166, s10, v150
	v_fmac_f32_e32 v167, s11, v151
	v_readlane_b32 s25, v52, 23
	v_readlane_b32 s26, v53, 23
	v_readlane_b32 s27, v54, 23
	v_readlane_b32 s28, v55, 23
	v_fmac_f32_e32 v164, s25, v152
	v_fmac_f32_e32 v165, s26, v153
	v_fmac_f32_e32 v166, s27, v154
	v_fmac_f32_e32 v167, s28, v155
	v_readlane_b32 s8, v52, 24
	v_readlane_b32 s9, v53, 24
	v_readlane_b32 s10, v54, 24
	v_readlane_b32 s11, v55, 24
	v_fmac_f32_e32 v164, s8, v156
	v_fmac_f32_e32 v165, s9, v157
	v_fmac_f32_e32 v166, s10, v158
	v_fmac_f32_e32 v167, s11, v159
	v_readlane_b32 s8, v56, 0
	v_readlane_b32 s9, v57, 0
	v_readlane_b32 s10, v58, 0
	v_readlane_b32 s11, v59, 0
	v_rcp_f32_e32 v174, s8
	v_rcp_f32_e32 v175, s9
	v_rcp_f32_e32 v176, s10
	v_rcp_f32_e32 v177, s11
	v_mul_f32_e32 v160, v160, v174
	v_mul_f32_e32 v161, v161, v175
	v_mul_f32_e32 v162, v162, v176
	v_mul_f32_e32 v163, v163, v177
	v_cmp_lt_f32_e64 s[2:3], 0, s8
	s_nop 1
	v_cndmask_b32_e64 v160, 0, v160, s[2:3]
	v_cmp_lt_f32_e64 s[2:3], 0, s9
	s_nop 1
	v_cndmask_b32_e64 v161, 0, v161, s[2:3]
	v_cmp_lt_f32_e64 s[2:3], 0, s10
	s_nop 1
	v_cndmask_b32_e64 v162, 0, v162, s[2:3]
	v_cmp_lt_f32_e64 s[2:3], 0, s11
	s_nop 1
	v_cndmask_b32_e64 v163, 0, v163, s[2:3]
	v_readlane_b32 s25, v56, 16
	v_readlane_b32 s26, v57, 16
	v_readlane_b32 s27, v58, 16
	v_readlane_b32 s28, v59, 16
	v_rcp_f32_e32 v174, s25
	v_rcp_f32_e32 v175, s26
	v_rcp_f32_e32 v176, s27
	v_rcp_f32_e32 v177, s28
	v_mul_f32_e32 v164, v164, v174
	v_mul_f32_e32 v165, v165, v175
	v_mul_f32_e32 v166, v166, v176
	v_mul_f32_e32 v167, v167, v177
	v_cmp_lt_f32_e64 s[2:3], 0, s25
	s_nop 1
	v_cndmask_b32_e64 v164, 0, v164, s[2:3]
	v_cmp_lt_f32_e64 s[2:3], 0, s26
	s_nop 1
	v_cndmask_b32_e64 v165, 0, v165, s[2:3]
	v_cmp_lt_f32_e64 s[2:3], 0, s27
	s_nop 1
	v_cndmask_b32_e64 v166, 0, v166, s[2:3]
	v_cmp_lt_f32_e64 s[2:3], 0, s28
	s_nop 1
	v_cndmask_b32_e64 v167, 0, v167, s[2:3]
	v_mul_f32_e32 v168, 0xbfb8aa3b, v168
	v_exp_f32_e32 v168, v168
	s_nop 0
	v_add_f32_e32 v168, 1.0, v168
	v_rcp_f32_e32 v168, v168
	s_lshr_b32 s2, s20, 1
	s_add_i32 s2, s2, 0x4000
	s_lshl_b32 s3, s2, 11
	s_and_b32 s6, s20, 1
	s_lshl_b32 s6, s6, 9
	s_add_i32 s3, s3, s6
	s_add_u32 s6, s19, 0x20700000
	s_addc_u32 s7, s22, 0
	s_add_u32 s6, s6, s3
	s_addc_u32 s7, s7, 0
	v_lshlrev_b32_e32 v43, 1, v18
	v_readlane_b32 s8, v168, 0
	v_readlane_b32 s9, v168, 1
	v_readlane_b32 s10, v168, 2
	s_nop 1
	v_mul_f32_e32 v176, s8, v170
	v_fmac_f32_e32 v176, s9, v160
	v_fmac_f32_e32 v176, s10, v164
	v_bfe_u32 v180, v176, 16, 1
	v_add3_u32 v176, v176, v180, s15
	global_store_short_d16_hi v43, v176, s[6:7] offset:0
	v_readlane_b32 s8, v168, 3
	v_readlane_b32 s9, v168, 4
	v_readlane_b32 s10, v168, 5
	s_nop 1
	v_mul_f32_e32 v177, s8, v171
	v_fmac_f32_e32 v177, s9, v161
	v_fmac_f32_e32 v177, s10, v165
	v_bfe_u32 v180, v177, 16, 1
	v_add3_u32 v177, v177, v180, s15
	global_store_short_d16_hi v43, v177, s[6:7] offset:128
	v_readlane_b32 s8, v168, 6
	v_readlane_b32 s9, v168, 7
	v_readlane_b32 s10, v168, 8
	s_nop 1
	v_mul_f32_e32 v178, s8, v172
	v_fmac_f32_e32 v178, s9, v162
	v_fmac_f32_e32 v178, s10, v166
	v_bfe_u32 v180, v178, 16, 1
	v_add3_u32 v178, v178, v180, s15
	global_store_short_d16_hi v43, v178, s[6:7] offset:256
	v_readlane_b32 s8, v168, 9
	v_readlane_b32 s9, v168, 10
	v_readlane_b32 s10, v168, 11
	s_nop 1
	v_mul_f32_e32 v179, s8, v173
	v_fmac_f32_e32 v179, s9, v163
	v_fmac_f32_e32 v179, s10, v167
	v_bfe_u32 v180, v179, 16, 1
	v_add3_u32 v179, v179, v180, s15
	global_store_short_d16_hi v43, v179, s[6:7] offset:384
	s_add_i32 s20, s20, s39
	s_cmpk_lt_i32 s20, 0x100
	s_cbranch_scc1 .Lsc_loop
